# G3/G5 loops get the same steady-state form: one barrier per slice, waves 4-7 on the rotated stream, no tail conditions until the last two iterations
# speedup vs baseline: 1.0126x; 1.0032x over previous
.LBB0_119:
	s_or_b64 exec, exec, s[20:21]
	v_mov_b32_e32 v18, 0
	v_mov_b32_e32 v34, 0
	v_add_u32_e32 v142, 0x800, v141
	s_mov_b64 s[20:21], 0
	s_mov_b32 s8, 3
	v_cmp_lt_i32_e32 vcc, 3, v136
	s_cbranch_vccnz .Lgr_G5x_entry
	s_branch .Lgf_G5x_top
.Lgf_G5x_top:
	s_waitcnt vmcnt(3)
	s_waitcnt lgkmcnt(0)
	s_barrier
	v_mfma_f32_16x16x32_bf16 v[102:105], v[2:5], v[26:29], v[102:105]
	v_mfma_f32_16x16x32_bf16 v[98:101], v[6:9], v[26:29], v[98:101]
	s_add_i32 s17, s8, -3
	s_and_b32 s19, s17, 2
	s_mulk_i32 s19, 0x6000
	v_add_u32_e32 v110, s19, v142
	ds_read_b128 v[106:109], v110
	v_mfma_f32_16x16x32_bf16 v[86:89], v[10:13], v[26:29], v[86:89]
	ds_read_b128 v[144:147], v110 offset:1024
	s_and_b32 s89, s8, 3
	s_mulk_i32 s89, 0x6000
	s_add_i32 s89, s89, s88
	s_mov_b32 m0, s89
	v_mfma_f32_16x16x32_bf16 v[70:73], v[14:17], v[26:29], v[70:73]
	v_mfma_f32_16x16x32_bf16 v[90:93], v[2:5], v[22:25], v[90:93]
	global_load_lds_dwordx4 v126, s[90:91]
	s_add_i32 m0, s89, 0x2000
	v_mfma_f32_16x16x32_bf16 v[78:81], v[6:9], v[22:25], v[78:81]
	global_load_lds_dwordx4 v128, s[90:91]
	s_add_i32 m0, s89, 0x4000
	v_mfma_f32_16x16x32_bf16 v[62:65], v[10:13], v[22:25], v[62:65]
	global_load_lds_dwordx4 v130, s[92:93]
	s_add_u32 s90, s90, 64
	s_addc_u32 s91, s91, 0
	s_add_u32 s92, s92, 64
	s_addc_u32 s93, s93, 0
	v_mfma_f32_16x16x32_bf16 v[50:53], v[14:17], v[22:25], v[50:53]
	s_waitcnt lgkmcnt(0)
	v_mfma_f32_16x16x32_bf16 v[74:77], v[2:5], v[106:109], v[74:77]
	s_add_i32 s26, s8, -2
	s_and_b32 s28, s26, 3
	s_mulk_i32 s28, 0x6000
	v_add_u32_e32 v127, s28, v140
	v_add_u32_e32 v143, s28, v141
	ds_read_b128 v[26:29], v143
	v_mfma_f32_16x16x32_bf16 v[58:61], v[6:9], v[106:109], v[58:61]
	ds_read_b128 v[22:25], v143 offset:1024
	v_mfma_f32_16x16x32_bf16 v[38:41], v[10:13], v[106:109], v[38:41]
	ds_read_b128 v[118:121], v127
	v_mfma_f32_16x16x32_bf16 v[30:33], v[14:17], v[106:109], v[30:33]
	ds_read_b128 v[114:117], v127 offset:1024
	ds_read_b128 v[110:113], v127 offset:2048
	ds_read_b128 v[106:109], v127 offset:3072
	v_mfma_f32_16x16x32_bf16 v[94:97], v[2:5], v[144:147], v[94:97]
	v_mfma_f32_16x16x32_bf16 v[82:85], v[6:9], v[144:147], v[82:85]
	v_mfma_f32_16x16x32_bf16 v[66:69], v[10:13], v[144:147], v[66:69]
	v_mfma_f32_16x16x32_bf16 v[34:37], v[14:17], v[144:147], v[34:37]
	s_waitcnt vmcnt(3)
	s_waitcnt lgkmcnt(0)
	s_barrier
	v_mfma_f32_16x16x32_bf16 v[102:105], v[118:121], v[26:29], v[102:105]
	v_mfma_f32_16x16x32_bf16 v[98:101], v[114:117], v[26:29], v[98:101]
	v_add_u32_e32 v132, s28, v142
	ds_read_b128 v[144:147], v132
	v_mfma_f32_16x16x32_bf16 v[86:89], v[110:113], v[26:29], v[86:89]
	ds_read_b128 v[122:125], v132 offset:1024
	s_add_i32 s89, s19, s88
	s_mov_b32 m0, s89
	v_mfma_f32_16x16x32_bf16 v[70:73], v[106:109], v[26:29], v[70:73]
	v_mfma_f32_16x16x32_bf16 v[90:93], v[118:121], v[22:25], v[90:93]
	global_load_lds_dwordx4 v126, s[90:91]
	s_add_i32 m0, s89, 0x2000
	v_mfma_f32_16x16x32_bf16 v[78:81], v[114:117], v[22:25], v[78:81]
	global_load_lds_dwordx4 v128, s[90:91]
	s_add_i32 m0, s89, 0x4000
	v_mfma_f32_16x16x32_bf16 v[62:65], v[110:113], v[22:25], v[62:65]
	global_load_lds_dwordx4 v130, s[92:93]
	s_add_u32 s90, s90, 64
	s_addc_u32 s91, s91, 0
	s_add_u32 s92, s92, 64
	s_addc_u32 s93, s93, 0
	v_mfma_f32_16x16x32_bf16 v[50:53], v[106:109], v[22:25], v[50:53]
	s_waitcnt lgkmcnt(0)
	v_mfma_f32_16x16x32_bf16 v[74:77], v[118:121], v[144:147], v[74:77]
	s_add_i32 s19, s8, -1
	s_and_b32 s19, s19, 2
	s_mulk_i32 s19, 0x6000
	v_add_u32_e32 v127, s19, v140
	v_add_u32_e32 v132, s19, v141
	ds_read_b128 v[26:29], v132
	v_mfma_f32_16x16x32_bf16 v[58:61], v[114:117], v[144:147], v[58:61]
	ds_read_b128 v[22:25], v132 offset:1024
	v_mfma_f32_16x16x32_bf16 v[38:41], v[110:113], v[144:147], v[38:41]
	ds_read_b128 v[2:5], v127
	v_mfma_f32_16x16x32_bf16 v[30:33], v[106:109], v[144:147], v[30:33]
	ds_read_b128 v[6:9], v127 offset:1024
	ds_read_b128 v[10:13], v127 offset:2048
	ds_read_b128 v[14:17], v127 offset:3072
	s_add_u32 s20, s20, 0x80
	s_addc_u32 s21, s21, 0
	s_add_i32 s8, s8, 2
	s_cmpk_gt_u32 s17, 0x55
	v_mfma_f32_16x16x32_bf16 v[94:97], v[118:121], v[122:125], v[94:97]
	v_mfma_f32_16x16x32_bf16 v[82:85], v[114:117], v[122:125], v[82:85]
	v_mfma_f32_16x16x32_bf16 v[66:69], v[110:113], v[122:125], v[66:69]
	v_mfma_f32_16x16x32_bf16 v[34:37], v[106:109], v[122:125], v[34:37]
	s_cmp_lt_u32 s8, 86
	s_cbranch_scc1 .Lgf_G5x_top
	s_branch .LBB0_121
.Lgr_G5x_entry:
	s_waitcnt vmcnt(3)
	s_waitcnt lgkmcnt(0)
	s_barrier
	v_mfma_f32_16x16x32_bf16 v[102:105], v[2:5], v[26:29], v[102:105]
	v_mfma_f32_16x16x32_bf16 v[98:101], v[6:9], v[26:29], v[98:101]
	s_add_i32 s17, s8, -3
	s_and_b32 s19, s17, 2
	s_mulk_i32 s19, 0x6000
	v_add_u32_e32 v110, s19, v142
	ds_read_b128 v[106:109], v110
	v_mfma_f32_16x16x32_bf16 v[86:89], v[10:13], v[26:29], v[86:89]
	ds_read_b128 v[144:147], v110 offset:1024
	s_and_b32 s89, s8, 3
	s_mulk_i32 s89, 0x6000
	s_add_i32 s89, s89, s88
	s_mov_b32 m0, s89
	v_mfma_f32_16x16x32_bf16 v[70:73], v[14:17], v[26:29], v[70:73]
	v_mfma_f32_16x16x32_bf16 v[90:93], v[2:5], v[22:25], v[90:93]
	global_load_lds_dwordx4 v126, s[90:91]
	s_add_i32 m0, s89, 0x2000
	v_mfma_f32_16x16x32_bf16 v[78:81], v[6:9], v[22:25], v[78:81]
	global_load_lds_dwordx4 v128, s[90:91]
	s_add_i32 m0, s89, 0x4000
	v_mfma_f32_16x16x32_bf16 v[62:65], v[10:13], v[22:25], v[62:65]
	global_load_lds_dwordx4 v130, s[92:93]
	s_add_u32 s90, s90, 64
	s_addc_u32 s91, s91, 0
	s_add_u32 s92, s92, 64
	s_addc_u32 s93, s93, 0
	v_mfma_f32_16x16x32_bf16 v[50:53], v[14:17], v[22:25], v[50:53]
	s_waitcnt vmcnt(3)
	s_waitcnt lgkmcnt(0)
	s_barrier
	v_mfma_f32_16x16x32_bf16 v[74:77], v[2:5], v[106:109], v[74:77]
	s_add_i32 s26, s8, -2
	s_and_b32 s28, s26, 3
	s_mulk_i32 s28, 0x6000
	v_add_u32_e32 v127, s28, v140
	v_add_u32_e32 v143, s28, v141
	ds_read_b128 v[26:29], v143
	v_mfma_f32_16x16x32_bf16 v[58:61], v[6:9], v[106:109], v[58:61]
	ds_read_b128 v[22:25], v143 offset:1024
	v_mfma_f32_16x16x32_bf16 v[38:41], v[10:13], v[106:109], v[38:41]
	ds_read_b128 v[118:121], v127
	v_mfma_f32_16x16x32_bf16 v[30:33], v[14:17], v[106:109], v[30:33]
	ds_read_b128 v[114:117], v127 offset:1024
	ds_read_b128 v[110:113], v127 offset:2048
	ds_read_b128 v[106:109], v127 offset:3072
	v_mfma_f32_16x16x32_bf16 v[94:97], v[2:5], v[144:147], v[94:97]
	v_mfma_f32_16x16x32_bf16 v[82:85], v[6:9], v[144:147], v[82:85]
	v_mfma_f32_16x16x32_bf16 v[66:69], v[10:13], v[144:147], v[66:69]
	v_mfma_f32_16x16x32_bf16 v[34:37], v[14:17], v[144:147], v[34:37]
	s_waitcnt lgkmcnt(0)
	v_mfma_f32_16x16x32_bf16 v[102:105], v[118:121], v[26:29], v[102:105]
	v_mfma_f32_16x16x32_bf16 v[98:101], v[114:117], v[26:29], v[98:101]
	v_add_u32_e32 v132, s28, v142
	ds_read_b128 v[144:147], v132
	v_mfma_f32_16x16x32_bf16 v[86:89], v[110:113], v[26:29], v[86:89]
	ds_read_b128 v[122:125], v132 offset:1024
	s_add_i32 s89, s19, s88
	s_mov_b32 m0, s89
	v_mfma_f32_16x16x32_bf16 v[70:73], v[106:109], v[26:29], v[70:73]
	v_mfma_f32_16x16x32_bf16 v[90:93], v[118:121], v[22:25], v[90:93]
	global_load_lds_dwordx4 v126, s[90:91]
	s_add_i32 m0, s89, 0x2000
	v_mfma_f32_16x16x32_bf16 v[78:81], v[114:117], v[22:25], v[78:81]
	global_load_lds_dwordx4 v128, s[90:91]
	s_add_i32 m0, s89, 0x4000
	v_mfma_f32_16x16x32_bf16 v[62:65], v[110:113], v[22:25], v[62:65]
	global_load_lds_dwordx4 v130, s[92:93]
	s_add_u32 s90, s90, 64
	s_addc_u32 s91, s91, 0
	s_add_u32 s92, s92, 64
	s_addc_u32 s93, s93, 0
	v_mfma_f32_16x16x32_bf16 v[50:53], v[106:109], v[22:25], v[50:53]
.Lgr_G5x_top:
	s_waitcnt vmcnt(3)
	s_waitcnt lgkmcnt(0)
	s_barrier
	v_mfma_f32_16x16x32_bf16 v[74:77], v[118:121], v[144:147], v[74:77]
	s_add_i32 s19, s8, -1
	s_and_b32 s19, s19, 2
	s_mulk_i32 s19, 0x6000
	v_add_u32_e32 v127, s19, v140
	v_add_u32_e32 v132, s19, v141
	ds_read_b128 v[26:29], v132
	v_mfma_f32_16x16x32_bf16 v[58:61], v[114:117], v[144:147], v[58:61]
	ds_read_b128 v[22:25], v132 offset:1024
	v_mfma_f32_16x16x32_bf16 v[38:41], v[110:113], v[144:147], v[38:41]
	ds_read_b128 v[2:5], v127
	v_mfma_f32_16x16x32_bf16 v[30:33], v[106:109], v[144:147], v[30:33]
	ds_read_b128 v[6:9], v127 offset:1024
	ds_read_b128 v[10:13], v127 offset:2048
	ds_read_b128 v[14:17], v127 offset:3072
	s_add_u32 s20, s20, 0x80
	s_addc_u32 s21, s21, 0
	s_add_i32 s8, s8, 2
	s_cmpk_gt_u32 s17, 0x55
	v_mfma_f32_16x16x32_bf16 v[94:97], v[118:121], v[122:125], v[94:97]
	v_mfma_f32_16x16x32_bf16 v[82:85], v[114:117], v[122:125], v[82:85]
	v_mfma_f32_16x16x32_bf16 v[66:69], v[110:113], v[122:125], v[66:69]
	v_mfma_f32_16x16x32_bf16 v[34:37], v[106:109], v[122:125], v[34:37]
	s_cmp_lt_u32 s8, 86
	s_cbranch_scc0 .LBB0_121
	s_waitcnt lgkmcnt(0)
	v_mfma_f32_16x16x32_bf16 v[102:105], v[2:5], v[26:29], v[102:105]
	v_mfma_f32_16x16x32_bf16 v[98:101], v[6:9], v[26:29], v[98:101]
	s_add_i32 s17, s8, -3
	s_and_b32 s19, s17, 2
	s_mulk_i32 s19, 0x6000
	v_add_u32_e32 v110, s19, v142
	ds_read_b128 v[106:109], v110
	v_mfma_f32_16x16x32_bf16 v[86:89], v[10:13], v[26:29], v[86:89]
	ds_read_b128 v[144:147], v110 offset:1024
	s_and_b32 s89, s8, 3
	s_mulk_i32 s89, 0x6000
	s_add_i32 s89, s89, s88
	s_mov_b32 m0, s89
	v_mfma_f32_16x16x32_bf16 v[70:73], v[14:17], v[26:29], v[70:73]
	v_mfma_f32_16x16x32_bf16 v[90:93], v[2:5], v[22:25], v[90:93]
	global_load_lds_dwordx4 v126, s[90:91]
	s_add_i32 m0, s89, 0x2000
	v_mfma_f32_16x16x32_bf16 v[78:81], v[6:9], v[22:25], v[78:81]
	global_load_lds_dwordx4 v128, s[90:91]
	s_add_i32 m0, s89, 0x4000
	v_mfma_f32_16x16x32_bf16 v[62:65], v[10:13], v[22:25], v[62:65]
	global_load_lds_dwordx4 v130, s[92:93]
	s_add_u32 s90, s90, 64
	s_addc_u32 s91, s91, 0
	s_add_u32 s92, s92, 64
	s_addc_u32 s93, s93, 0
	v_mfma_f32_16x16x32_bf16 v[50:53], v[14:17], v[22:25], v[50:53]
	s_waitcnt vmcnt(3)
	s_waitcnt lgkmcnt(0)
	s_barrier
	v_mfma_f32_16x16x32_bf16 v[74:77], v[2:5], v[106:109], v[74:77]
	s_add_i32 s26, s8, -2
	s_and_b32 s28, s26, 3
	s_mulk_i32 s28, 0x6000
	v_add_u32_e32 v127, s28, v140
	v_add_u32_e32 v143, s28, v141
	ds_read_b128 v[26:29], v143
	v_mfma_f32_16x16x32_bf16 v[58:61], v[6:9], v[106:109], v[58:61]
	ds_read_b128 v[22:25], v143 offset:1024
	v_mfma_f32_16x16x32_bf16 v[38:41], v[10:13], v[106:109], v[38:41]
	ds_read_b128 v[118:121], v127
	v_mfma_f32_16x16x32_bf16 v[30:33], v[14:17], v[106:109], v[30:33]
	ds_read_b128 v[114:117], v127 offset:1024
	ds_read_b128 v[110:113], v127 offset:2048
	ds_read_b128 v[106:109], v127 offset:3072
	v_mfma_f32_16x16x32_bf16 v[94:97], v[2:5], v[144:147], v[94:97]
	v_mfma_f32_16x16x32_bf16 v[82:85], v[6:9], v[144:147], v[82:85]
	v_mfma_f32_16x16x32_bf16 v[66:69], v[10:13], v[144:147], v[66:69]
	v_mfma_f32_16x16x32_bf16 v[34:37], v[14:17], v[144:147], v[34:37]
	s_waitcnt lgkmcnt(0)
	v_mfma_f32_16x16x32_bf16 v[102:105], v[118:121], v[26:29], v[102:105]
	v_mfma_f32_16x16x32_bf16 v[98:101], v[114:117], v[26:29], v[98:101]
	v_add_u32_e32 v132, s28, v142
	ds_read_b128 v[144:147], v132
	v_mfma_f32_16x16x32_bf16 v[86:89], v[110:113], v[26:29], v[86:89]
	ds_read_b128 v[122:125], v132 offset:1024
	s_add_i32 s89, s19, s88
	s_mov_b32 m0, s89
	v_mfma_f32_16x16x32_bf16 v[70:73], v[106:109], v[26:29], v[70:73]
	v_mfma_f32_16x16x32_bf16 v[90:93], v[118:121], v[22:25], v[90:93]
	global_load_lds_dwordx4 v126, s[90:91]
	s_add_i32 m0, s89, 0x2000
	v_mfma_f32_16x16x32_bf16 v[78:81], v[114:117], v[22:25], v[78:81]
	global_load_lds_dwordx4 v128, s[90:91]
	s_add_i32 m0, s89, 0x4000
	v_mfma_f32_16x16x32_bf16 v[62:65], v[110:113], v[22:25], v[62:65]
	global_load_lds_dwordx4 v130, s[92:93]
	s_add_u32 s90, s90, 64
	s_addc_u32 s91, s91, 0
	s_add_u32 s92, s92, 64
	s_addc_u32 s93, s93, 0
	v_mfma_f32_16x16x32_bf16 v[50:53], v[106:109], v[22:25], v[50:53]
	s_branch .Lgr_G5x_top

.Lgf_G3x_top:
	s_waitcnt vmcnt(3)
	s_waitcnt lgkmcnt(0)
	s_barrier
	v_mfma_f32_16x16x32_bf16 v[102:105], v[2:5], v[26:29], v[102:105]
	v_mfma_f32_16x16x32_bf16 v[98:101], v[6:9], v[26:29], v[98:101]
	s_add_i32 s17, s8, -3
	s_and_b32 s19, s17, 2
	s_mulk_i32 s19, 0x6000
	v_add_u32_e32 v110, s19, v142
	ds_read_b128 v[106:109], v110
	v_mfma_f32_16x16x32_bf16 v[86:89], v[10:13], v[26:29], v[86:89]
	ds_read_b128 v[144:147], v110 offset:1024
	s_and_b32 s69, s8, 3
	s_mulk_i32 s69, 0x6000
	s_add_i32 s69, s69, s29
	s_mov_b32 m0, s69
	v_mfma_f32_16x16x32_bf16 v[70:73], v[14:17], v[26:29], v[70:73]
	v_mfma_f32_16x16x32_bf16 v[90:93], v[2:5], v[22:25], v[90:93]
	global_load_lds_dwordx4 v126, s[44:45]
	s_add_i32 m0, s69, 0x2000
	v_mfma_f32_16x16x32_bf16 v[78:81], v[6:9], v[22:25], v[78:81]
	global_load_lds_dwordx4 v128, s[44:45]
	s_add_i32 m0, s69, 0x4000
	v_mfma_f32_16x16x32_bf16 v[62:65], v[10:13], v[22:25], v[62:65]
	global_load_lds_dwordx4 v130, s[30:31]
	s_add_u32 s44, s44, 64
	s_addc_u32 s45, s45, 0
	s_add_u32 s30, s30, 64
	s_addc_u32 s31, s31, 0
	v_mfma_f32_16x16x32_bf16 v[46:49], v[14:17], v[22:25], v[46:49]
	s_waitcnt lgkmcnt(0)
	v_mfma_f32_16x16x32_bf16 v[74:77], v[2:5], v[106:109], v[74:77]
	s_add_i32 s26, s8, -2
	s_and_b32 s28, s26, 3
	s_mulk_i32 s28, 0x6000
	v_add_u32_e32 v127, s28, v140
	v_add_u32_e32 v143, s28, v141
	ds_read_b128 v[26:29], v143
	v_mfma_f32_16x16x32_bf16 v[58:61], v[6:9], v[106:109], v[58:61]
	ds_read_b128 v[22:25], v143 offset:1024
	v_mfma_f32_16x16x32_bf16 v[38:41], v[10:13], v[106:109], v[38:41]
	ds_read_b128 v[118:121], v127
	v_mfma_f32_16x16x32_bf16 v[30:33], v[14:17], v[106:109], v[30:33]
	ds_read_b128 v[114:117], v127 offset:1024
	ds_read_b128 v[110:113], v127 offset:2048
	ds_read_b128 v[106:109], v127 offset:3072
	v_mfma_f32_16x16x32_bf16 v[94:97], v[2:5], v[144:147], v[94:97]
	v_mfma_f32_16x16x32_bf16 v[82:85], v[6:9], v[144:147], v[82:85]
	v_mfma_f32_16x16x32_bf16 v[66:69], v[10:13], v[144:147], v[66:69]
	v_mfma_f32_16x16x32_bf16 v[34:37], v[14:17], v[144:147], v[34:37]
	s_waitcnt vmcnt(3)
	s_waitcnt lgkmcnt(0)
	s_barrier
	v_mfma_f32_16x16x32_bf16 v[102:105], v[118:121], v[26:29], v[102:105]
	v_mfma_f32_16x16x32_bf16 v[98:101], v[114:117], v[26:29], v[98:101]
	v_add_u32_e32 v132, s28, v142
	ds_read_b128 v[144:147], v132
	v_mfma_f32_16x16x32_bf16 v[86:89], v[110:113], v[26:29], v[86:89]
	ds_read_b128 v[122:125], v132 offset:1024
	s_add_i32 s69, s19, s29
	s_mov_b32 m0, s69
	v_mfma_f32_16x16x32_bf16 v[70:73], v[106:109], v[26:29], v[70:73]
	v_mfma_f32_16x16x32_bf16 v[90:93], v[118:121], v[22:25], v[90:93]
	global_load_lds_dwordx4 v126, s[44:45]
	s_add_i32 m0, s69, 0x2000
	v_mfma_f32_16x16x32_bf16 v[78:81], v[114:117], v[22:25], v[78:81]
	global_load_lds_dwordx4 v128, s[44:45]
	s_add_i32 m0, s69, 0x4000
	v_mfma_f32_16x16x32_bf16 v[62:65], v[110:113], v[22:25], v[62:65]
	global_load_lds_dwordx4 v130, s[30:31]
	s_add_u32 s44, s44, 64
	s_addc_u32 s45, s45, 0
	s_add_u32 s30, s30, 64
	s_addc_u32 s31, s31, 0
	v_mfma_f32_16x16x32_bf16 v[46:49], v[106:109], v[22:25], v[46:49]
	s_waitcnt lgkmcnt(0)
	v_mfma_f32_16x16x32_bf16 v[74:77], v[118:121], v[144:147], v[74:77]
	s_add_i32 s19, s8, -1
	s_and_b32 s19, s19, 2
	s_mulk_i32 s19, 0x6000
	v_add_u32_e32 v127, s19, v140
	v_add_u32_e32 v132, s19, v141
	ds_read_b128 v[26:29], v132
	v_mfma_f32_16x16x32_bf16 v[58:61], v[114:117], v[144:147], v[58:61]
	ds_read_b128 v[22:25], v132 offset:1024
	v_mfma_f32_16x16x32_bf16 v[38:41], v[110:113], v[144:147], v[38:41]
	ds_read_b128 v[2:5], v127
	v_mfma_f32_16x16x32_bf16 v[30:33], v[106:109], v[144:147], v[30:33]
	ds_read_b128 v[6:9], v127 offset:1024
	ds_read_b128 v[10:13], v127 offset:2048
	ds_read_b128 v[14:17], v127 offset:3072
	s_add_u32 s20, s20, 0x80
	s_addc_u32 s21, s21, 0
	s_add_i32 s8, s8, 2
	s_cmp_gt_u32 s17, 29
	v_mfma_f32_16x16x32_bf16 v[94:97], v[118:121], v[122:125], v[94:97]
	v_mfma_f32_16x16x32_bf16 v[82:85], v[114:117], v[122:125], v[82:85]
	v_mfma_f32_16x16x32_bf16 v[66:69], v[110:113], v[122:125], v[66:69]
	v_mfma_f32_16x16x32_bf16 v[34:37], v[106:109], v[122:125], v[34:37]
	s_cmp_lt_u32 s8, 30
	s_cbranch_scc1 .Lgf_G3x_top
	s_branch .LBB0_291
.Lgr_G3x_entry:
	s_waitcnt vmcnt(3)
	s_waitcnt lgkmcnt(0)
	s_barrier
	v_mfma_f32_16x16x32_bf16 v[102:105], v[2:5], v[26:29], v[102:105]
	v_mfma_f32_16x16x32_bf16 v[98:101], v[6:9], v[26:29], v[98:101]
	s_add_i32 s17, s8, -3
	s_and_b32 s19, s17, 2
	s_mulk_i32 s19, 0x6000
	v_add_u32_e32 v110, s19, v142
	ds_read_b128 v[106:109], v110
	v_mfma_f32_16x16x32_bf16 v[86:89], v[10:13], v[26:29], v[86:89]
	ds_read_b128 v[144:147], v110 offset:1024
	s_and_b32 s69, s8, 3
	s_mulk_i32 s69, 0x6000
	s_add_i32 s69, s69, s29
	s_mov_b32 m0, s69
	v_mfma_f32_16x16x32_bf16 v[70:73], v[14:17], v[26:29], v[70:73]
	v_mfma_f32_16x16x32_bf16 v[90:93], v[2:5], v[22:25], v[90:93]
	global_load_lds_dwordx4 v126, s[44:45]
	s_add_i32 m0, s69, 0x2000
	v_mfma_f32_16x16x32_bf16 v[78:81], v[6:9], v[22:25], v[78:81]
	global_load_lds_dwordx4 v128, s[44:45]
	s_add_i32 m0, s69, 0x4000
	v_mfma_f32_16x16x32_bf16 v[62:65], v[10:13], v[22:25], v[62:65]
	global_load_lds_dwordx4 v130, s[30:31]
	s_add_u32 s44, s44, 64
	s_addc_u32 s45, s45, 0
	s_add_u32 s30, s30, 64
	s_addc_u32 s31, s31, 0
	v_mfma_f32_16x16x32_bf16 v[46:49], v[14:17], v[22:25], v[46:49]
	s_waitcnt vmcnt(3)
	s_waitcnt lgkmcnt(0)
	s_barrier
	v_mfma_f32_16x16x32_bf16 v[74:77], v[2:5], v[106:109], v[74:77]
	s_add_i32 s26, s8, -2
	s_and_b32 s28, s26, 3
	s_mulk_i32 s28, 0x6000
	v_add_u32_e32 v127, s28, v140
	v_add_u32_e32 v143, s28, v141
	ds_read_b128 v[26:29], v143
	v_mfma_f32_16x16x32_bf16 v[58:61], v[6:9], v[106:109], v[58:61]
	ds_read_b128 v[22:25], v143 offset:1024
	v_mfma_f32_16x16x32_bf16 v[38:41], v[10:13], v[106:109], v[38:41]
	ds_read_b128 v[118:121], v127
	v_mfma_f32_16x16x32_bf16 v[30:33], v[14:17], v[106:109], v[30:33]
	ds_read_b128 v[114:117], v127 offset:1024
	ds_read_b128 v[110:113], v127 offset:2048
	ds_read_b128 v[106:109], v127 offset:3072
	v_mfma_f32_16x16x32_bf16 v[94:97], v[2:5], v[144:147], v[94:97]
	v_mfma_f32_16x16x32_bf16 v[82:85], v[6:9], v[144:147], v[82:85]
	v_mfma_f32_16x16x32_bf16 v[66:69], v[10:13], v[144:147], v[66:69]
	v_mfma_f32_16x16x32_bf16 v[34:37], v[14:17], v[144:147], v[34:37]
	s_waitcnt lgkmcnt(0)
	v_mfma_f32_16x16x32_bf16 v[102:105], v[118:121], v[26:29], v[102:105]
	v_mfma_f32_16x16x32_bf16 v[98:101], v[114:117], v[26:29], v[98:101]
	v_add_u32_e32 v132, s28, v142
	ds_read_b128 v[144:147], v132
	v_mfma_f32_16x16x32_bf16 v[86:89], v[110:113], v[26:29], v[86:89]
	ds_read_b128 v[122:125], v132 offset:1024
	s_add_i32 s69, s19, s29
	s_mov_b32 m0, s69
	v_mfma_f32_16x16x32_bf16 v[70:73], v[106:109], v[26:29], v[70:73]
	v_mfma_f32_16x16x32_bf16 v[90:93], v[118:121], v[22:25], v[90:93]
	global_load_lds_dwordx4 v126, s[44:45]
	s_add_i32 m0, s69, 0x2000
	v_mfma_f32_16x16x32_bf16 v[78:81], v[114:117], v[22:25], v[78:81]
	global_load_lds_dwordx4 v128, s[44:45]
	s_add_i32 m0, s69, 0x4000
	v_mfma_f32_16x16x32_bf16 v[62:65], v[110:113], v[22:25], v[62:65]
	global_load_lds_dwordx4 v130, s[30:31]
	s_add_u32 s44, s44, 64
	s_addc_u32 s45, s45, 0
	s_add_u32 s30, s30, 64
	s_addc_u32 s31, s31, 0
	v_mfma_f32_16x16x32_bf16 v[46:49], v[106:109], v[22:25], v[46:49]
.Lgr_G3x_top:
	s_waitcnt vmcnt(3)
	s_waitcnt lgkmcnt(0)
	s_barrier
	v_mfma_f32_16x16x32_bf16 v[74:77], v[118:121], v[144:147], v[74:77]
	s_add_i32 s19, s8, -1
	s_and_b32 s19, s19, 2
	s_mulk_i32 s19, 0x6000
	v_add_u32_e32 v127, s19, v140
	v_add_u32_e32 v132, s19, v141
	ds_read_b128 v[26:29], v132
	v_mfma_f32_16x16x32_bf16 v[58:61], v[114:117], v[144:147], v[58:61]
	ds_read_b128 v[22:25], v132 offset:1024
	v_mfma_f32_16x16x32_bf16 v[38:41], v[110:113], v[144:147], v[38:41]
	ds_read_b128 v[2:5], v127
	v_mfma_f32_16x16x32_bf16 v[30:33], v[106:109], v[144:147], v[30:33]
	ds_read_b128 v[6:9], v127 offset:1024
	ds_read_b128 v[10:13], v127 offset:2048
	ds_read_b128 v[14:17], v127 offset:3072
	s_add_u32 s20, s20, 0x80
	s_addc_u32 s21, s21, 0
	s_add_i32 s8, s8, 2
	s_cmp_gt_u32 s17, 29
	v_mfma_f32_16x16x32_bf16 v[94:97], v[118:121], v[122:125], v[94:97]
	v_mfma_f32_16x16x32_bf16 v[82:85], v[114:117], v[122:125], v[82:85]
	v_mfma_f32_16x16x32_bf16 v[66:69], v[110:113], v[122:125], v[66:69]
	v_mfma_f32_16x16x32_bf16 v[34:37], v[106:109], v[122:125], v[34:37]
	s_cmp_lt_u32 s8, 30
	s_cbranch_scc0 .LBB0_291
	s_waitcnt lgkmcnt(0)
	v_mfma_f32_16x16x32_bf16 v[102:105], v[2:5], v[26:29], v[102:105]
	v_mfma_f32_16x16x32_bf16 v[98:101], v[6:9], v[26:29], v[98:101]
	s_add_i32 s17, s8, -3
	s_and_b32 s19, s17, 2
	s_mulk_i32 s19, 0x6000
	v_add_u32_e32 v110, s19, v142
	ds_read_b128 v[106:109], v110
	v_mfma_f32_16x16x32_bf16 v[86:89], v[10:13], v[26:29], v[86:89]
	ds_read_b128 v[144:147], v110 offset:1024
	s_and_b32 s69, s8, 3
	s_mulk_i32 s69, 0x6000
	s_add_i32 s69, s69, s29
	s_mov_b32 m0, s69
	v_mfma_f32_16x16x32_bf16 v[70:73], v[14:17], v[26:29], v[70:73]
	v_mfma_f32_16x16x32_bf16 v[90:93], v[2:5], v[22:25], v[90:93]
	global_load_lds_dwordx4 v126, s[44:45]
	s_add_i32 m0, s69, 0x2000
	v_mfma_f32_16x16x32_bf16 v[78:81], v[6:9], v[22:25], v[78:81]
	global_load_lds_dwordx4 v128, s[44:45]
	s_add_i32 m0, s69, 0x4000
	v_mfma_f32_16x16x32_bf16 v[62:65], v[10:13], v[22:25], v[62:65]
	global_load_lds_dwordx4 v130, s[30:31]
	s_add_u32 s44, s44, 64
	s_addc_u32 s45, s45, 0
	s_add_u32 s30, s30, 64
	s_addc_u32 s31, s31, 0
	v_mfma_f32_16x16x32_bf16 v[46:49], v[14:17], v[22:25], v[46:49]
	s_waitcnt vmcnt(3)
	s_waitcnt lgkmcnt(0)
	s_barrier
	v_mfma_f32_16x16x32_bf16 v[74:77], v[2:5], v[106:109], v[74:77]
	s_add_i32 s26, s8, -2
	s_and_b32 s28, s26, 3
	s_mulk_i32 s28, 0x6000
	v_add_u32_e32 v127, s28, v140
	v_add_u32_e32 v143, s28, v141
	ds_read_b128 v[26:29], v143
	v_mfma_f32_16x16x32_bf16 v[58:61], v[6:9], v[106:109], v[58:61]
	ds_read_b128 v[22:25], v143 offset:1024
	v_mfma_f32_16x16x32_bf16 v[38:41], v[10:13], v[106:109], v[38:41]
	ds_read_b128 v[118:121], v127
	v_mfma_f32_16x16x32_bf16 v[30:33], v[14:17], v[106:109], v[30:33]
	ds_read_b128 v[114:117], v127 offset:1024
	ds_read_b128 v[110:113], v127 offset:2048
	ds_read_b128 v[106:109], v127 offset:3072
	v_mfma_f32_16x16x32_bf16 v[94:97], v[2:5], v[144:147], v[94:97]
	v_mfma_f32_16x16x32_bf16 v[82:85], v[6:9], v[144:147], v[82:85]
	v_mfma_f32_16x16x32_bf16 v[66:69], v[10:13], v[144:147], v[66:69]
	v_mfma_f32_16x16x32_bf16 v[34:37], v[14:17], v[144:147], v[34:37]
	s_waitcnt lgkmcnt(0)
	v_mfma_f32_16x16x32_bf16 v[102:105], v[118:121], v[26:29], v[102:105]
	v_mfma_f32_16x16x32_bf16 v[98:101], v[114:117], v[26:29], v[98:101]
	v_add_u32_e32 v132, s28, v142
	ds_read_b128 v[144:147], v132
	v_mfma_f32_16x16x32_bf16 v[86:89], v[110:113], v[26:29], v[86:89]
	ds_read_b128 v[122:125], v132 offset:1024
	s_add_i32 s69, s19, s29
	s_mov_b32 m0, s69
	v_mfma_f32_16x16x32_bf16 v[70:73], v[106:109], v[26:29], v[70:73]
	v_mfma_f32_16x16x32_bf16 v[90:93], v[118:121], v[22:25], v[90:93]
	global_load_lds_dwordx4 v126, s[44:45]
	s_add_i32 m0, s69, 0x2000
	v_mfma_f32_16x16x32_bf16 v[78:81], v[114:117], v[22:25], v[78:81]
	global_load_lds_dwordx4 v128, s[44:45]
	s_add_i32 m0, s69, 0x4000
	v_mfma_f32_16x16x32_bf16 v[62:65], v[110:113], v[22:25], v[62:65]
	global_load_lds_dwordx4 v130, s[30:31]
	s_add_u32 s44, s44, 64
	s_addc_u32 s45, s45, 0
	s_add_u32 s30, s30, 64
	s_addc_u32 s31, s31, 0
	v_mfma_f32_16x16x32_bf16 v[46:49], v[106:109], v[22:25], v[46:49]
	s_branch .Lgr_G3x_top
